# v21 + nt (streaming) policy on the in-proj and residual epilogue stores
# speedup vs baseline: 1.0195x; 1.0020x over previous
;     __device__ __forceinline__ void operator()(const f32x4 (&acc)[2][2][4][2], const Unit& u, int wr, int wc, int fr, int fq) const {
;     ...
;                 const int row = row0 + ai * HALF + m * 16;
;                 const int tk = row & 8191, tp = (tk & ~2047) | ((tk & 15) << 7) | ((tk & 2047) >> 4);
;                 if (u.pn >= 8) {
;                     const f32x4 p0 = hv[0][0] * hv[1][0], p1 = hv[0][1] * hv[1][1];
;                     u32x4 w; w.x = cvt_pk_bf16(p0[0], p0[1]); w.y = cvt_pk_bf16(p0[2], p0[3]); w.z = cvt_pk_bf16(p1[0], p1[1]); w.w = cvt_pk_bf16(p1[2], p1[3]);
;                     *(u32x4*)(O + (size_t)row * ldc + 512 + 128 * (u.pn - 8) + 32 * wc + 8 * fq) = w;
;                     continue;
;                 }
;                 const size_t hrow = (size_t)((row >> 13) * 8 + (u.pn & 1) * 4 + wc) * 8192 + tp;
;                 bf16_t* rowp = u.pn < 2 ? QKV + hrow * 64 + 8 * fq : u.pn < 6 ? QKV + (size_t)4 * 8 * 8192 * 64 + hrow * 128 + ((u.pn >> 1) - 1) * 64 + 8 * fq
;                                         : O + (size_t)row * ldc + (col0 - 1536);
; #pragma unroll
;                 for (int bj = 0; bj < 2; ++bj) {
;                     const f32x4 v0 = hv[bj][0] * (gv[bj][0] * rs), v1 = hv[bj][1] * (gv[bj][1] * rs);
;                     u32x4 w; w.x = cvt_pk_bf16(v0[0], v0[1]); w.y = cvt_pk_bf16(v0[2], v0[3]); w.z = cvt_pk_bf16(v1[0], v1[1]); w.w = cvt_pk_bf16(v1[2], v1[3]);
;                     *(u32x4*)(rowp + 32 * bj) = w;
;                 }
.LBB0_160:
	v_pk_mul_f32 v[200:201], v[50:51], v[198:199] op_sel_hi:[1,0]
	v_pk_mul_f32 v[216:217], v[48:49], v[198:199] op_sel_hi:[1,0]
	v_pk_mul_f32 v[218:219], v[54:55], v[198:199] op_sel_hi:[1,0]
	v_pk_mul_f32 v[220:221], v[52:53], v[198:199] op_sel_hi:[1,0]
	v_pk_mul_f32 v[200:201], v[158:159], v[200:201]
	v_pk_mul_f32 v[216:217], v[156:157], v[216:217]
	v_pk_mul_f32 v[230:231], v[154:155], v[218:219]
	v_pk_mul_f32 v[218:219], v[152:153], v[220:221]
	v_cvt_pk_bf16_f32 v216, v216, v217
	v_cvt_pk_bf16_f32 v217, v200, v201
	v_cvt_pk_bf16_f32 v218, v218, v219
	v_cvt_pk_bf16_f32 v219, v230, v231
	global_store_dwordx4 v[144:145], v[216:219], off nt
	v_pk_mul_f32 v[200:201], v[58:59], v[198:199] op_sel_hi:[1,0]
	v_pk_mul_f32 v[220:221], v[60:61], v[198:199] op_sel_hi:[1,0]
	v_pk_mul_f32 v[216:217], v[56:57], v[198:199] op_sel_hi:[1,0]
	v_pk_mul_f32 v[218:219], v[62:63], v[198:199] op_sel_hi:[1,0]
	v_pk_mul_f32 v[200:201], v[150:151], v[200:201]
	v_pk_mul_f32 v[216:217], v[148:149], v[216:217]
	v_pk_mul_f32 v[230:231], v[146:147], v[218:219]
	v_pk_mul_f32 v[218:219], v[196:197], v[220:221]
	v_cvt_pk_bf16_f32 v216, v216, v217
	v_cvt_pk_bf16_f32 v217, v200, v201
	v_cvt_pk_bf16_f32 v218, v218, v219
	v_cvt_pk_bf16_f32 v219, v230, v231
	s_mov_b64 s[38:39], 0
	global_store_dwordx4 v[144:145], v[216:219], off offset:64 nt
.LBB0_161:
	s_lshl_b32 s10, s40, 7
	s_add_i32 s60, s10, 0xfffffc00
	s_ashr_i32 s61, s60, 31
	s_and_b64 vcc, exec, s[38:39]
	v_lshlrev_b32_e32 v144, 1, v186
	s_cbranch_vccz .LBB0_163
	v_pk_mul_f32 v[150:151], v[158:159], v[150:151]
	v_pk_mul_f32 v[154:155], v[154:155], v[146:147]
	v_cvt_pk_bf16_f32 v147, v150, v151
	v_lshlrev_b64 v[150:151], 11, v[194:195]
	v_lshl_add_u64 v[150:151], s[28:29], 0, v[150:151]
	v_lshl_add_u64 v[150:151], s[60:61], 1, v[150:151]
	s_lshl_b32 s12, s65, 1
	v_pk_mul_f32 v[148:149], v[156:157], v[148:149]
	v_pk_mul_f32 v[152:153], v[152:153], v[196:197]
	v_lshl_add_u64 v[150:151], v[150:151], 0, s[12:13]
	v_mov_b32_e32 v145, v169
	v_cvt_pk_bf16_f32 v146, v148, v149
	v_cvt_pk_bf16_f32 v148, v152, v153
	v_cvt_pk_bf16_f32 v149, v154, v155
	v_lshl_add_u64 v[150:151], v[150:151], 0, v[144:145]
	global_store_dwordx4 v[150:151], v[146:149], off offset:1024 nt

;     __device__ __forceinline__ void operator()(const f32x4 (&acc)[2][2][4][2], const Unit& u, int wr, int wc, int fr, int fq) const {
;     ...
;                 const int row = row0 + ai * HALF + m * 16;
;                 const int tk = row & 8191, tp = (tk & ~2047) | ((tk & 15) << 7) | ((tk & 2047) >> 4);
;                 if (u.pn >= 8) {
;                     const f32x4 p0 = hv[0][0] * hv[1][0], p1 = hv[0][1] * hv[1][1];
;                     u32x4 w; w.x = cvt_pk_bf16(p0[0], p0[1]); w.y = cvt_pk_bf16(p0[2], p0[3]); w.z = cvt_pk_bf16(p1[0], p1[1]); w.w = cvt_pk_bf16(p1[2], p1[3]);
;                     *(u32x4*)(O + (size_t)row * ldc + 512 + 128 * (u.pn - 8) + 32 * wc + 8 * fq) = w;
;                     continue;
;                 }
;                 const size_t hrow = (size_t)((row >> 13) * 8 + (u.pn & 1) * 4 + wc) * 8192 + tp;
;                 bf16_t* rowp = u.pn < 2 ? QKV + hrow * 64 + 8 * fq : u.pn < 6 ? QKV + (size_t)4 * 8 * 8192 * 64 + hrow * 128 + ((u.pn >> 1) - 1) * 64 + 8 * fq
;                                         : O + (size_t)row * ldc + (col0 - 1536);
; #pragma unroll
;                 for (int bj = 0; bj < 2; ++bj) {
;                     const f32x4 v0 = hv[bj][0] * (gv[bj][0] * rs), v1 = hv[bj][1] * (gv[bj][1] * rs);
;                     u32x4 w; w.x = cvt_pk_bf16(v0[0], v0[1]); w.y = cvt_pk_bf16(v0[2], v0[3]); w.z = cvt_pk_bf16(v1[0], v1[1]); w.w = cvt_pk_bf16(v1[2], v1[3]);
;                     *(u32x4*)(rowp + 32 * bj) = w;
;                 }
.LBB0_175:
	v_pk_mul_f32 v[152:153], v[50:51], v[148:149] op_sel_hi:[1,0]
	v_pk_mul_f32 v[154:155], v[48:49], v[148:149] op_sel_hi:[1,0]
	v_pk_mul_f32 v[156:157], v[142:143], v[152:153]
	v_pk_mul_f32 v[152:153], v[140:141], v[154:155]
	v_pk_mul_f32 v[154:155], v[54:55], v[148:149] op_sel_hi:[1,0]
	v_pk_mul_f32 v[158:159], v[52:53], v[148:149] op_sel_hi:[1,0]
	v_pk_mul_f32 v[196:197], v[138:139], v[154:155]
	v_pk_mul_f32 v[154:155], v[136:137], v[158:159]
	v_cvt_pk_bf16_f32 v152, v152, v153
	v_cvt_pk_bf16_f32 v153, v156, v157
	v_cvt_pk_bf16_f32 v154, v154, v155
	v_cvt_pk_bf16_f32 v155, v196, v197
	global_store_dwordx4 v[150:151], v[152:155], off nt
	s_mov_b64 s[24:25], 0
	s_nop 0
	v_pk_mul_f32 v[152:153], v[58:59], v[148:149] op_sel_hi:[1,0]
	v_pk_mul_f32 v[154:155], v[56:57], v[148:149] op_sel_hi:[1,0]
	v_pk_mul_f32 v[156:157], v[134:135], v[152:153]
	v_pk_mul_f32 v[152:153], v[132:133], v[154:155]
	v_pk_mul_f32 v[154:155], v[62:63], v[148:149] op_sel_hi:[1,0]
	v_pk_mul_f32 v[148:149], v[60:61], v[148:149] op_sel_hi:[1,0]
	v_pk_mul_f32 v[158:159], v[130:131], v[154:155]
	v_pk_mul_f32 v[148:149], v[128:129], v[148:149]
	v_cvt_pk_bf16_f32 v152, v152, v153
	v_cvt_pk_bf16_f32 v153, v156, v157
	v_cvt_pk_bf16_f32 v154, v148, v149
	v_cvt_pk_bf16_f32 v155, v158, v159
	global_store_dwordx4 v[150:151], v[152:155], off offset:64 nt
.LBB0_176:
	s_and_b64 vcc, exec, s[24:25]
	s_cbranch_vccz .LBB0_178
	v_pk_mul_f32 v[132:133], v[140:141], v[132:133]
	v_pk_mul_f32 v[138:139], v[138:139], v[130:131]
	v_pk_mul_f32 v[130:131], v[136:137], v[128:129]
	v_cvt_pk_bf16_f32 v128, v132, v133
	v_lshlrev_b64 v[132:133], 11, v[146:147]
	v_lshl_add_u64 v[132:133], s[28:29], 0, v[132:133]
	v_lshl_add_u64 v[132:133], s[60:61], 1, v[132:133]
	s_lshl_b32 s12, s65, 1
	v_pk_mul_f32 v[134:135], v[142:143], v[134:135]
	v_lshl_add_u64 v[132:133], v[132:133], 0, s[12:13]
	v_mov_b32_e32 v145, v169
	v_cvt_pk_bf16_f32 v129, v134, v135
	v_cvt_pk_bf16_f32 v130, v130, v131
	v_cvt_pk_bf16_f32 v131, v138, v139
	v_lshl_add_u64 v[132:133], v[132:133], 0, v[144:145]
	global_store_dwordx4 v[132:133], v[128:131], off offset:1024 nt

;     __device__ __forceinline__ void operator()(const f32x4 (&acc)[2][2][4][2], const Unit& u, int wr, int wc, int fr, int fq) const {
;     ...
;                 const int row = row0 + ai * HALF + m * 16;
;                 const int tk = row & 8191, tp = (tk & ~2047) | ((tk & 15) << 7) | ((tk & 2047) >> 4);
;                 if (u.pn >= 8) {
;                     const f32x4 p0 = hv[0][0] * hv[1][0], p1 = hv[0][1] * hv[1][1];
;                     u32x4 w; w.x = cvt_pk_bf16(p0[0], p0[1]); w.y = cvt_pk_bf16(p0[2], p0[3]); w.z = cvt_pk_bf16(p1[0], p1[1]); w.w = cvt_pk_bf16(p1[2], p1[3]);
;                     *(u32x4*)(O + (size_t)row * ldc + 512 + 128 * (u.pn - 8) + 32 * wc + 8 * fq) = w;
;                     continue;
;                 }
;                 const size_t hrow = (size_t)((row >> 13) * 8 + (u.pn & 1) * 4 + wc) * 8192 + tp;
;                 bf16_t* rowp = u.pn < 2 ? QKV + hrow * 64 + 8 * fq : u.pn < 6 ? QKV + (size_t)4 * 8 * 8192 * 64 + hrow * 128 + ((u.pn >> 1) - 1) * 64 + 8 * fq
;                                         : O + (size_t)row * ldc + (col0 - 1536);
; #pragma unroll
;                 for (int bj = 0; bj < 2; ++bj) {
;                     const f32x4 v0 = hv[bj][0] * (gv[bj][0] * rs), v1 = hv[bj][1] * (gv[bj][1] * rs);
;                     u32x4 w; w.x = cvt_pk_bf16(v0[0], v0[1]); w.y = cvt_pk_bf16(v0[2], v0[3]); w.z = cvt_pk_bf16(v1[0], v1[1]); w.w = cvt_pk_bf16(v1[2], v1[3]);
;                     *(u32x4*)(rowp + 32 * bj) = w;
;                 }
.LBB0_190:
	v_pk_mul_f32 v[134:135], v[50:51], v[130:131] op_sel_hi:[1,0]
	v_pk_mul_f32 v[136:137], v[48:49], v[130:131] op_sel_hi:[1,0]
	v_pk_mul_f32 v[138:139], v[126:127], v[134:135]
	v_pk_mul_f32 v[134:135], v[124:125], v[136:137]
	v_pk_mul_f32 v[136:137], v[54:55], v[130:131] op_sel_hi:[1,0]
	v_pk_mul_f32 v[140:141], v[52:53], v[130:131] op_sel_hi:[1,0]
	v_pk_mul_f32 v[142:143], v[122:123], v[136:137]
	v_pk_mul_f32 v[136:137], v[120:121], v[140:141]
	v_cvt_pk_bf16_f32 v134, v134, v135
	v_cvt_pk_bf16_f32 v135, v138, v139
	v_cvt_pk_bf16_f32 v136, v136, v137
	v_cvt_pk_bf16_f32 v137, v142, v143
	global_store_dwordx4 v[132:133], v[134:137], off nt
	s_mov_b64 s[24:25], 0
	s_nop 0
	v_pk_mul_f32 v[134:135], v[58:59], v[130:131] op_sel_hi:[1,0]
	v_pk_mul_f32 v[136:137], v[56:57], v[130:131] op_sel_hi:[1,0]
	v_pk_mul_f32 v[138:139], v[118:119], v[134:135]
	v_pk_mul_f32 v[134:135], v[116:117], v[136:137]
	v_pk_mul_f32 v[136:137], v[62:63], v[130:131] op_sel_hi:[1,0]
	v_pk_mul_f32 v[130:131], v[60:61], v[130:131] op_sel_hi:[1,0]
	v_pk_mul_f32 v[140:141], v[114:115], v[136:137]
	v_pk_mul_f32 v[130:131], v[112:113], v[130:131]
	v_cvt_pk_bf16_f32 v134, v134, v135
	v_cvt_pk_bf16_f32 v135, v138, v139
	v_cvt_pk_bf16_f32 v136, v130, v131
	v_cvt_pk_bf16_f32 v137, v140, v141
	global_store_dwordx4 v[132:133], v[134:137], off offset:64 nt
.LBB0_191:
	s_and_b64 vcc, exec, s[24:25]
	s_cbranch_vccz .LBB0_193
	v_pk_mul_f32 v[116:117], v[124:125], v[116:117]
	v_pk_mul_f32 v[122:123], v[122:123], v[114:115]
	v_pk_mul_f32 v[114:115], v[120:121], v[112:113]
	v_cvt_pk_bf16_f32 v112, v116, v117
	v_lshlrev_b64 v[116:117], 11, v[128:129]
	v_lshl_add_u64 v[116:117], s[28:29], 0, v[116:117]
	v_lshl_add_u64 v[116:117], s[60:61], 1, v[116:117]
	s_lshl_b32 s12, s65, 1
	v_pk_mul_f32 v[118:119], v[126:127], v[118:119]
	v_lshl_add_u64 v[116:117], v[116:117], 0, s[12:13]
	v_mov_b32_e32 v145, v169
	v_cvt_pk_bf16_f32 v113, v118, v119
	v_cvt_pk_bf16_f32 v114, v114, v115
	v_cvt_pk_bf16_f32 v115, v122, v123
	v_lshl_add_u64 v[116:117], v[116:117], 0, v[144:145]
	global_store_dwordx4 v[116:117], v[112:115], off offset:1024 nt

;     __device__ __forceinline__ void operator()(const f32x4 (&acc)[2][2][4][2], const Unit& u, int wr, int wc, int fr, int fq) const {
;     ...
;                 const int row = row0 + ai * HALF + m * 16;
;                 const int tk = row & 8191, tp = (tk & ~2047) | ((tk & 15) << 7) | ((tk & 2047) >> 4);
;                 if (u.pn >= 8) {
;                     const f32x4 p0 = hv[0][0] * hv[1][0], p1 = hv[0][1] * hv[1][1];
;                     u32x4 w; w.x = cvt_pk_bf16(p0[0], p0[1]); w.y = cvt_pk_bf16(p0[2], p0[3]); w.z = cvt_pk_bf16(p1[0], p1[1]); w.w = cvt_pk_bf16(p1[2], p1[3]);
;                     *(u32x4*)(O + (size_t)row * ldc + 512 + 128 * (u.pn - 8) + 32 * wc + 8 * fq) = w;
;                     continue;
;                 }
;                 const size_t hrow = (size_t)((row >> 13) * 8 + (u.pn & 1) * 4 + wc) * 8192 + tp;
;                 bf16_t* rowp = u.pn < 2 ? QKV + hrow * 64 + 8 * fq : u.pn < 6 ? QKV + (size_t)4 * 8 * 8192 * 64 + hrow * 128 + ((u.pn >> 1) - 1) * 64 + 8 * fq
;                                         : O + (size_t)row * ldc + (col0 - 1536);
; #pragma unroll
;                 for (int bj = 0; bj < 2; ++bj) {
;                     const f32x4 v0 = hv[bj][0] * (gv[bj][0] * rs), v1 = hv[bj][1] * (gv[bj][1] * rs);
;                     u32x4 w; w.x = cvt_pk_bf16(v0[0], v0[1]); w.y = cvt_pk_bf16(v0[2], v0[3]); w.z = cvt_pk_bf16(v1[0], v1[1]); w.w = cvt_pk_bf16(v1[2], v1[3]);
;                     *(u32x4*)(rowp + 32 * bj) = w;
;                 }
.LBB0_205:
	v_pk_mul_f32 v[118:119], v[50:51], v[114:115] op_sel_hi:[1,0]
	v_pk_mul_f32 v[120:121], v[48:49], v[114:115] op_sel_hi:[1,0]
	v_pk_mul_f32 v[122:123], v[110:111], v[118:119]
	v_pk_mul_f32 v[118:119], v[108:109], v[120:121]
	v_pk_mul_f32 v[120:121], v[54:55], v[114:115] op_sel_hi:[1,0]
	v_pk_mul_f32 v[124:125], v[52:53], v[114:115] op_sel_hi:[1,0]
	v_pk_mul_f32 v[126:127], v[106:107], v[120:121]
	v_pk_mul_f32 v[120:121], v[104:105], v[124:125]
	v_cvt_pk_bf16_f32 v118, v118, v119
	v_cvt_pk_bf16_f32 v119, v122, v123
	v_cvt_pk_bf16_f32 v120, v120, v121
	v_cvt_pk_bf16_f32 v121, v126, v127
	global_store_dwordx4 v[116:117], v[118:121], off nt
	s_mov_b64 s[24:25], 0
	s_nop 0
	v_pk_mul_f32 v[118:119], v[58:59], v[114:115] op_sel_hi:[1,0]
	v_pk_mul_f32 v[120:121], v[56:57], v[114:115] op_sel_hi:[1,0]
	v_pk_mul_f32 v[122:123], v[102:103], v[118:119]
	v_pk_mul_f32 v[118:119], v[100:101], v[120:121]
	v_pk_mul_f32 v[120:121], v[62:63], v[114:115] op_sel_hi:[1,0]
	v_pk_mul_f32 v[114:115], v[60:61], v[114:115] op_sel_hi:[1,0]
	v_pk_mul_f32 v[124:125], v[98:99], v[120:121]
	v_pk_mul_f32 v[114:115], v[96:97], v[114:115]
	v_cvt_pk_bf16_f32 v118, v118, v119
	v_cvt_pk_bf16_f32 v119, v122, v123
	v_cvt_pk_bf16_f32 v120, v114, v115
	v_cvt_pk_bf16_f32 v121, v124, v125
	global_store_dwordx4 v[116:117], v[118:121], off offset:64 nt
.LBB0_206:
	s_and_b64 vcc, exec, s[24:25]
	s_cbranch_vccz .LBB0_208
	v_pk_mul_f32 v[100:101], v[108:109], v[100:101]
	v_pk_mul_f32 v[106:107], v[106:107], v[98:99]
	v_pk_mul_f32 v[98:99], v[104:105], v[96:97]
	v_cvt_pk_bf16_f32 v96, v100, v101
	v_lshlrev_b64 v[100:101], 11, v[112:113]
	v_lshl_add_u64 v[100:101], s[28:29], 0, v[100:101]
	v_lshl_add_u64 v[100:101], s[60:61], 1, v[100:101]
	s_lshl_b32 s12, s65, 1
	v_pk_mul_f32 v[102:103], v[110:111], v[102:103]
	v_lshl_add_u64 v[100:101], v[100:101], 0, s[12:13]
	v_mov_b32_e32 v145, v169
	v_cvt_pk_bf16_f32 v97, v102, v103
	v_cvt_pk_bf16_f32 v98, v98, v99
	v_cvt_pk_bf16_f32 v99, v106, v107
	v_lshl_add_u64 v[100:101], v[100:101], 0, v[144:145]
	global_store_dwordx4 v[100:101], v[96:99], off offset:1024 nt

;     __device__ __forceinline__ void operator()(const f32x4 (&acc)[2][2][4][2], const Unit& u, int wr, int wc, int fr, int fq) const {
;     ...
;                 const int row = row0 + ai * HALF + m * 16;
;                 const int tk = row & 8191, tp = (tk & ~2047) | ((tk & 15) << 7) | ((tk & 2047) >> 4);
;                 if (u.pn >= 8) {
;                     const f32x4 p0 = hv[0][0] * hv[1][0], p1 = hv[0][1] * hv[1][1];
;                     u32x4 w; w.x = cvt_pk_bf16(p0[0], p0[1]); w.y = cvt_pk_bf16(p0[2], p0[3]); w.z = cvt_pk_bf16(p1[0], p1[1]); w.w = cvt_pk_bf16(p1[2], p1[3]);
;                     *(u32x4*)(O + (size_t)row * ldc + 512 + 128 * (u.pn - 8) + 32 * wc + 8 * fq) = w;
;                     continue;
;                 }
;                 const size_t hrow = (size_t)((row >> 13) * 8 + (u.pn & 1) * 4 + wc) * 8192 + tp;
;                 bf16_t* rowp = u.pn < 2 ? QKV + hrow * 64 + 8 * fq : u.pn < 6 ? QKV + (size_t)4 * 8 * 8192 * 64 + hrow * 128 + ((u.pn >> 1) - 1) * 64 + 8 * fq
;                                         : O + (size_t)row * ldc + (col0 - 1536);
; #pragma unroll
;                 for (int bj = 0; bj < 2; ++bj) {
;                     const f32x4 v0 = hv[bj][0] * (gv[bj][0] * rs), v1 = hv[bj][1] * (gv[bj][1] * rs);
;                     u32x4 w; w.x = cvt_pk_bf16(v0[0], v0[1]); w.y = cvt_pk_bf16(v0[2], v0[3]); w.z = cvt_pk_bf16(v1[0], v1[1]); w.w = cvt_pk_bf16(v1[2], v1[3]);
;                     *(u32x4*)(rowp + 32 * bj) = w;
;                 }
.LBB0_220:
	v_pk_mul_f32 v[104:105], v[50:51], v[100:101] op_sel_hi:[1,0]
	v_pk_mul_f32 v[106:107], v[48:49], v[100:101] op_sel_hi:[1,0]
	v_pk_mul_f32 v[108:109], v[78:79], v[104:105]
	v_pk_mul_f32 v[104:105], v[76:77], v[106:107]
	v_pk_mul_f32 v[106:107], v[54:55], v[100:101] op_sel_hi:[1,0]
	v_pk_mul_f32 v[110:111], v[52:53], v[100:101] op_sel_hi:[1,0]
	v_pk_mul_f32 v[112:113], v[74:75], v[106:107]
	v_pk_mul_f32 v[106:107], v[72:73], v[110:111]
	v_cvt_pk_bf16_f32 v104, v104, v105
	v_cvt_pk_bf16_f32 v105, v108, v109
	v_cvt_pk_bf16_f32 v106, v106, v107
	v_cvt_pk_bf16_f32 v107, v112, v113
	global_store_dwordx4 v[102:103], v[104:107], off nt
	v_pk_mul_f32 v[110:111], v[60:61], v[100:101] op_sel_hi:[1,0]
	s_mov_b64 s[24:25], 0
	v_pk_mul_f32 v[104:105], v[58:59], v[100:101] op_sel_hi:[1,0]
	v_pk_mul_f32 v[106:107], v[56:57], v[100:101] op_sel_hi:[1,0]
	v_pk_mul_f32 v[108:109], v[70:71], v[104:105]
	v_pk_mul_f32 v[104:105], v[68:69], v[106:107]
	v_pk_mul_f32 v[106:107], v[62:63], v[100:101] op_sel_hi:[1,0]
	v_cvt_pk_bf16_f32 v104, v104, v105
	v_pk_mul_f32 v[112:113], v[66:67], v[106:107]
	v_pk_mul_f32 v[106:107], v[96:97], v[110:111]
	v_cvt_pk_bf16_f32 v105, v108, v109
	v_cvt_pk_bf16_f32 v106, v106, v107
	v_cvt_pk_bf16_f32 v107, v112, v113
	global_store_dwordx4 v[102:103], v[104:107], off offset:64 nt
.LBB0_221:
	s_and_b64 vcc, exec, s[24:25]
	s_cbranch_vccz .LBB0_223
	v_pk_mul_f32 v[70:71], v[78:79], v[70:71]
	v_pk_mul_f32 v[74:75], v[74:75], v[66:67]
	v_cvt_pk_bf16_f32 v67, v70, v71
	v_lshlrev_b64 v[70:71], 11, v[98:99]
	v_lshl_add_u64 v[70:71], s[28:29], 0, v[70:71]
	v_lshl_add_u64 v[70:71], s[60:61], 1, v[70:71]
	s_lshl_b32 s12, s65, 1
	v_pk_mul_f32 v[68:69], v[76:77], v[68:69]
	v_pk_mul_f32 v[72:73], v[72:73], v[96:97]
	v_lshl_add_u64 v[70:71], v[70:71], 0, s[12:13]
	v_mov_b32_e32 v145, v169
	v_cvt_pk_bf16_f32 v66, v68, v69
	v_cvt_pk_bf16_f32 v68, v72, v73
	v_cvt_pk_bf16_f32 v69, v74, v75
	v_lshl_add_u64 v[70:71], v[70:71], 0, v[144:145]
	global_store_dwordx4 v[70:71], v[66:69], off offset:1024 nt

;     __device__ __forceinline__ void operator()(const f32x4 (&acc)[2][2][4][2], const Unit& u, int wr, int wc, int fr, int fq) const {
;     ...
;                 const int row = row0 + ai * HALF + m * 16;
;                 const int tk = row & 8191, tp = (tk & ~2047) | ((tk & 15) << 7) | ((tk & 2047) >> 4);
;                 if (u.pn >= 8) {
;                     const f32x4 p0 = hv[0][0] * hv[1][0], p1 = hv[0][1] * hv[1][1];
;                     u32x4 w; w.x = cvt_pk_bf16(p0[0], p0[1]); w.y = cvt_pk_bf16(p0[2], p0[3]); w.z = cvt_pk_bf16(p1[0], p1[1]); w.w = cvt_pk_bf16(p1[2], p1[3]);
;                     *(u32x4*)(O + (size_t)row * ldc + 512 + 128 * (u.pn - 8) + 32 * wc + 8 * fq) = w;
;                     continue;
;                 }
;                 const size_t hrow = (size_t)((row >> 13) * 8 + (u.pn & 1) * 4 + wc) * 8192 + tp;
;                 bf16_t* rowp = u.pn < 2 ? QKV + hrow * 64 + 8 * fq : u.pn < 6 ? QKV + (size_t)4 * 8 * 8192 * 64 + hrow * 128 + ((u.pn >> 1) - 1) * 64 + 8 * fq
;                                         : O + (size_t)row * ldc + (col0 - 1536);
; #pragma unroll
;                 for (int bj = 0; bj < 2; ++bj) {
;                     const f32x4 v0 = hv[bj][0] * (gv[bj][0] * rs), v1 = hv[bj][1] * (gv[bj][1] * rs);
;                     u32x4 w; w.x = cvt_pk_bf16(v0[0], v0[1]); w.y = cvt_pk_bf16(v0[2], v0[3]); w.z = cvt_pk_bf16(v1[0], v1[1]); w.w = cvt_pk_bf16(v1[2], v1[3]);
;                     *(u32x4*)(rowp + 32 * bj) = w;
;                 }
.LBB0_235:
	v_pk_mul_f32 v[72:73], v[50:51], v[68:69] op_sel_hi:[1,0]
	v_pk_mul_f32 v[74:75], v[48:49], v[68:69] op_sel_hi:[1,0]
	v_pk_mul_f32 v[76:77], v[46:47], v[72:73]
	v_pk_mul_f32 v[72:73], v[44:45], v[74:75]
	v_pk_mul_f32 v[74:75], v[54:55], v[68:69] op_sel_hi:[1,0]
	v_pk_mul_f32 v[78:79], v[52:53], v[68:69] op_sel_hi:[1,0]
	v_pk_mul_f32 v[96:97], v[42:43], v[74:75]
	v_pk_mul_f32 v[74:75], v[40:41], v[78:79]
	v_cvt_pk_bf16_f32 v72, v72, v73
	v_cvt_pk_bf16_f32 v73, v76, v77
	v_cvt_pk_bf16_f32 v74, v74, v75
	v_cvt_pk_bf16_f32 v75, v96, v97
	global_store_dwordx4 v[70:71], v[72:75], off nt
	s_mov_b64 s[24:25], 0
	s_nop 0
	v_pk_mul_f32 v[72:73], v[58:59], v[68:69] op_sel_hi:[1,0]
	v_pk_mul_f32 v[74:75], v[56:57], v[68:69] op_sel_hi:[1,0]
	v_pk_mul_f32 v[76:77], v[38:39], v[72:73]
	v_pk_mul_f32 v[72:73], v[36:37], v[74:75]
	v_pk_mul_f32 v[74:75], v[62:63], v[68:69] op_sel_hi:[1,0]
	v_pk_mul_f32 v[68:69], v[60:61], v[68:69] op_sel_hi:[1,0]
	v_pk_mul_f32 v[78:79], v[34:35], v[74:75]
	v_pk_mul_f32 v[68:69], v[32:33], v[68:69]
	v_cvt_pk_bf16_f32 v72, v72, v73
	v_cvt_pk_bf16_f32 v73, v76, v77
	v_cvt_pk_bf16_f32 v74, v68, v69
	v_cvt_pk_bf16_f32 v75, v78, v79
	global_store_dwordx4 v[70:71], v[72:75], off offset:64 nt
.LBB0_236:
	s_and_b64 vcc, exec, s[24:25]
	s_cbranch_vccz .LBB0_238
	v_pk_mul_f32 v[36:37], v[44:45], v[36:37]
	v_pk_mul_f32 v[42:43], v[42:43], v[34:35]
	v_pk_mul_f32 v[34:35], v[40:41], v[32:33]
	v_cvt_pk_bf16_f32 v32, v36, v37
	v_lshlrev_b64 v[36:37], 11, v[66:67]
	v_lshl_add_u64 v[36:37], s[28:29], 0, v[36:37]
	v_lshl_add_u64 v[36:37], s[60:61], 1, v[36:37]
	s_lshl_b32 s12, s65, 1
	v_pk_mul_f32 v[38:39], v[46:47], v[38:39]
	v_lshl_add_u64 v[36:37], v[36:37], 0, s[12:13]
	v_mov_b32_e32 v145, v169
	v_cvt_pk_bf16_f32 v33, v38, v39
	v_cvt_pk_bf16_f32 v34, v34, v35
	v_cvt_pk_bf16_f32 v35, v42, v43
	v_lshl_add_u64 v[36:37], v[36:37], 0, v[144:145]
	global_store_dwordx4 v[36:37], v[32:35], off offset:1024 nt

;     __device__ __forceinline__ void operator()(const f32x4 (&acc)[2][2][4][2], const Unit& u, int wr, int wc, int fr, int fq) const {
;     ...
;                 const int row = row0 + ai * HALF + m * 16;
;                 const int tk = row & 8191, tp = (tk & ~2047) | ((tk & 15) << 7) | ((tk & 2047) >> 4);
;                 if (u.pn >= 8) {
;                     const f32x4 p0 = hv[0][0] * hv[1][0], p1 = hv[0][1] * hv[1][1];
;                     u32x4 w; w.x = cvt_pk_bf16(p0[0], p0[1]); w.y = cvt_pk_bf16(p0[2], p0[3]); w.z = cvt_pk_bf16(p1[0], p1[1]); w.w = cvt_pk_bf16(p1[2], p1[3]);
;                     *(u32x4*)(O + (size_t)row * ldc + 512 + 128 * (u.pn - 8) + 32 * wc + 8 * fq) = w;
;                     continue;
;                 }
;                 const size_t hrow = (size_t)((row >> 13) * 8 + (u.pn & 1) * 4 + wc) * 8192 + tp;
;                 bf16_t* rowp = u.pn < 2 ? QKV + hrow * 64 + 8 * fq : u.pn < 6 ? QKV + (size_t)4 * 8 * 8192 * 64 + hrow * 128 + ((u.pn >> 1) - 1) * 64 + 8 * fq
;                                         : O + (size_t)row * ldc + (col0 - 1536);
; #pragma unroll
;                 for (int bj = 0; bj < 2; ++bj) {
;                     const f32x4 v0 = hv[bj][0] * (gv[bj][0] * rs), v1 = hv[bj][1] * (gv[bj][1] * rs);
;                     u32x4 w; w.x = cvt_pk_bf16(v0[0], v0[1]); w.y = cvt_pk_bf16(v0[2], v0[3]); w.z = cvt_pk_bf16(v1[0], v1[1]); w.w = cvt_pk_bf16(v1[2], v1[3]);
;                     *(u32x4*)(rowp + 32 * bj) = w;
;                 }
.LBB0_250:
	v_pk_mul_f32 v[38:39], v[50:51], v[34:35] op_sel_hi:[1,0]
	v_pk_mul_f32 v[40:41], v[48:49], v[34:35] op_sel_hi:[1,0]
	v_pk_mul_f32 v[42:43], v[30:31], v[38:39]
	v_pk_mul_f32 v[38:39], v[28:29], v[40:41]
	v_pk_mul_f32 v[40:41], v[54:55], v[34:35] op_sel_hi:[1,0]
	v_pk_mul_f32 v[44:45], v[52:53], v[34:35] op_sel_hi:[1,0]
	v_pk_mul_f32 v[46:47], v[26:27], v[40:41]
	v_pk_mul_f32 v[40:41], v[24:25], v[44:45]
	v_cvt_pk_bf16_f32 v38, v38, v39
	v_cvt_pk_bf16_f32 v39, v42, v43
	v_cvt_pk_bf16_f32 v40, v40, v41
	v_cvt_pk_bf16_f32 v41, v46, v47
	global_store_dwordx4 v[36:37], v[38:41], off nt
	s_mov_b64 s[24:25], 0
	s_nop 0
	v_pk_mul_f32 v[38:39], v[58:59], v[34:35] op_sel_hi:[1,0]
	v_pk_mul_f32 v[40:41], v[56:57], v[34:35] op_sel_hi:[1,0]
	v_pk_mul_f32 v[42:43], v[22:23], v[38:39]
	v_pk_mul_f32 v[38:39], v[20:21], v[40:41]
	v_pk_mul_f32 v[40:41], v[62:63], v[34:35] op_sel_hi:[1,0]
	v_pk_mul_f32 v[34:35], v[60:61], v[34:35] op_sel_hi:[1,0]
	v_pk_mul_f32 v[44:45], v[18:19], v[40:41]
	v_pk_mul_f32 v[34:35], v[16:17], v[34:35]
	v_cvt_pk_bf16_f32 v38, v38, v39
	v_cvt_pk_bf16_f32 v39, v42, v43
	v_cvt_pk_bf16_f32 v40, v34, v35
	v_cvt_pk_bf16_f32 v41, v44, v45
	global_store_dwordx4 v[36:37], v[38:41], off offset:64 nt
.LBB0_251:
	s_and_b64 vcc, exec, s[24:25]
	s_cbranch_vccz .LBB0_253
	v_pk_mul_f32 v[20:21], v[28:29], v[20:21]
	v_pk_mul_f32 v[26:27], v[26:27], v[18:19]
	v_pk_mul_f32 v[18:19], v[24:25], v[16:17]
	v_cvt_pk_bf16_f32 v16, v20, v21
	v_lshlrev_b64 v[20:21], 11, v[32:33]
	v_lshl_add_u64 v[20:21], s[28:29], 0, v[20:21]
	v_lshl_add_u64 v[20:21], s[60:61], 1, v[20:21]
	s_lshl_b32 s12, s65, 1
	v_pk_mul_f32 v[22:23], v[30:31], v[22:23]
	v_lshl_add_u64 v[20:21], v[20:21], 0, s[12:13]
	v_mov_b32_e32 v145, v169
	v_cvt_pk_bf16_f32 v17, v22, v23
	v_cvt_pk_bf16_f32 v18, v18, v19
	v_cvt_pk_bf16_f32 v19, v26, v27
	v_lshl_add_u64 v[20:21], v[20:21], 0, v[144:145]
	global_store_dwordx4 v[20:21], v[16:19], off offset:1024 nt

;     __device__ __forceinline__ void operator()(const f32x4 (&acc)[2][2][4][2], const Unit& u, int wr, int wc, int fr, int fq) const {
;     ...
;                 const int row = row0 + ai * HALF + m * 16;
;                 const int tk = row & 8191, tp = (tk & ~2047) | ((tk & 15) << 7) | ((tk & 2047) >> 4);
;                 if (u.pn >= 8) {
;                     const f32x4 p0 = hv[0][0] * hv[1][0], p1 = hv[0][1] * hv[1][1];
;                     u32x4 w; w.x = cvt_pk_bf16(p0[0], p0[1]); w.y = cvt_pk_bf16(p0[2], p0[3]); w.z = cvt_pk_bf16(p1[0], p1[1]); w.w = cvt_pk_bf16(p1[2], p1[3]);
;                     *(u32x4*)(O + (size_t)row * ldc + 512 + 128 * (u.pn - 8) + 32 * wc + 8 * fq) = w;
;                     continue;
;                 }
;                 const size_t hrow = (size_t)((row >> 13) * 8 + (u.pn & 1) * 4 + wc) * 8192 + tp;
;                 bf16_t* rowp = u.pn < 2 ? QKV + hrow * 64 + 8 * fq : u.pn < 6 ? QKV + (size_t)4 * 8 * 8192 * 64 + hrow * 128 + ((u.pn >> 1) - 1) * 64 + 8 * fq
;                                         : O + (size_t)row * ldc + (col0 - 1536);
; #pragma unroll
;                 for (int bj = 0; bj < 2; ++bj) {
;                     const f32x4 v0 = hv[bj][0] * (gv[bj][0] * rs), v1 = hv[bj][1] * (gv[bj][1] * rs);
;                     u32x4 w; w.x = cvt_pk_bf16(v0[0], v0[1]); w.y = cvt_pk_bf16(v0[2], v0[3]); w.z = cvt_pk_bf16(v1[0], v1[1]); w.w = cvt_pk_bf16(v1[2], v1[3]);
;                     *(u32x4*)(rowp + 32 * bj) = w;
;                 }
.LBB0_267:
	v_pk_mul_f32 v[22:23], v[50:51], v[18:19] op_sel_hi:[1,0]
	v_pk_mul_f32 v[24:25], v[48:49], v[18:19] op_sel_hi:[1,0]
	v_pk_mul_f32 v[26:27], v[14:15], v[22:23]
	v_pk_mul_f32 v[22:23], v[12:13], v[24:25]
	v_pk_mul_f32 v[24:25], v[54:55], v[18:19] op_sel_hi:[1,0]
	v_pk_mul_f32 v[28:29], v[52:53], v[18:19] op_sel_hi:[1,0]
	v_pk_mul_f32 v[30:31], v[10:11], v[24:25]
	v_pk_mul_f32 v[24:25], v[8:9], v[28:29]
	v_cvt_pk_bf16_f32 v22, v22, v23
	v_cvt_pk_bf16_f32 v23, v26, v27
	v_cvt_pk_bf16_f32 v24, v24, v25
	v_cvt_pk_bf16_f32 v25, v30, v31
	global_store_dwordx4 v[20:21], v[22:25], off nt
	s_nop 1
	v_pk_mul_f32 v[22:23], v[58:59], v[18:19] op_sel_hi:[1,0]
	v_pk_mul_f32 v[24:25], v[56:57], v[18:19] op_sel_hi:[1,0]
	v_pk_mul_f32 v[26:27], v[6:7], v[22:23]
	v_pk_mul_f32 v[22:23], v[4:5], v[24:25]
	v_pk_mul_f32 v[24:25], v[62:63], v[18:19] op_sel_hi:[1,0]
	v_pk_mul_f32 v[18:19], v[60:61], v[18:19] op_sel_hi:[1,0]
	v_pk_mul_f32 v[28:29], v[2:3], v[24:25]
	v_pk_mul_f32 v[18:19], v[0:1], v[18:19]
	v_cvt_pk_bf16_f32 v22, v22, v23
	v_cvt_pk_bf16_f32 v23, v26, v27
	v_cvt_pk_bf16_f32 v24, v18, v19
	v_cvt_pk_bf16_f32 v25, v28, v29
	global_store_dwordx4 v[20:21], v[22:25], off offset:64 nt
	s_branch .LBB0_258
.LBB0_268:
	v_pk_mul_f32 v[4:5], v[12:13], v[4:5]
	v_pk_mul_f32 v[10:11], v[10:11], v[2:3]
	v_pk_mul_f32 v[2:3], v[8:9], v[0:1]
	v_cvt_pk_bf16_f32 v0, v4, v5
	v_lshlrev_b64 v[4:5], 11, v[16:17]
	v_lshl_add_u64 v[4:5], s[28:29], 0, v[4:5]
	v_lshl_add_u64 v[4:5], s[60:61], 1, v[4:5]
	s_lshl_b32 s12, s65, 1
	v_pk_mul_f32 v[6:7], v[14:15], v[6:7]
	v_lshl_add_u64 v[4:5], v[4:5], 0, s[12:13]
	v_mov_b32_e32 v145, v169
	v_cvt_pk_bf16_f32 v1, v6, v7
	v_cvt_pk_bf16_f32 v2, v2, v3
	v_cvt_pk_bf16_f32 v3, v10, v11
	v_lshl_add_u64 v[4:5], v[4:5], 0, v[144:145]
	global_store_dwordx4 v[4:5], v[0:3], off offset:1024 nt
	s_and_b64 vcc, exec, s[0:1]
	s_mov_b64 s[0:1], -1
	s_cbranch_vccnz .LBB0_124

;     __device__ __forceinline__ void operator()(const f32x4 (&acc)[2][2][4][2], const Unit& u, int wr, int wc, int fr, int fq) const {
;     ...
;         const PG8_GAS bf16_t* xinb = (const PG8_GAS bf16_t*)pp->xinb; PG8_GAS float* out = (PG8_GAS float*)pp->out; PG8_GAS bf16_t* outb = (PG8_GAS bf16_t*)pp->outb; const PG8_GAS float* gate = (const PG8_GAS float*)pp->gate;
;         PG8_GAS float* rss = (PG8_GAS float*)pp->rss; const float gs = pp->gs; const int flags = pp->flags; const bool has = flags & 1, outf = flags & 4;
;         const int b = (u.pm * BM) >> 13;
;         const PG8_GAS float* gp = gate + (size_t)b * 9216;
;         const int row0 = u.pm * BM + wr * 64 + fr, col0 = u.pn * BM + wc * 32 + 8 * fq;
;         f32x4 gv[2][2];
; #pragma unroll
;         for (int bj = 0; bj < 2; ++bj)
; #pragma unroll
;             for (int n = 0; n < 2; ++n) gv[bj][n] = *(const PG8_GAS f32x4*)(gp + col0 + bj * HALF + n * 4) * gs;
; #pragma unroll
;         for (int ai = 0; ai < 2; ++ai) {
;             u32x4 xa[2][4][2];
; #pragma unroll
;             for (int m = 0; m < 4; ++m)
; #pragma unroll
;                 for (int bj = 0; bj < 2; ++bj) xa[ai][m][bj] = *(const PG8_GAS u32x4*)(xinb + (size_t)(row0 + ai * HALF + m * 16) * 1024 + col0 + bj * HALF);
; #pragma unroll
;             for (int m = 0; m < 4; ++m) { const int row = row0 + ai * HALF + m * 16; const size_t off = (size_t)row * 1024 + col0; float ss = 0.f;
; #pragma unroll
;                 for (int bj = 0; bj < 2; ++bj) {
;                     const u32x4 t = xa[ai][m][bj];
;                     const f32x4 x0 = (f32x4){__uint_as_float(t.x << 16), __uint_as_float(t.x & 0xffff0000u), __uint_as_float(t.y << 16), __uint_as_float(t.y & 0xffff0000u)};
;                     const f32x4 x1 = (f32x4){__uint_as_float(t.z << 16), __uint_as_float(t.z & 0xffff0000u), __uint_as_float(t.w << 16), __uint_as_float(t.w & 0xffff0000u)};
;                     const f32x4 o0 = x0 + gv[bj][0] * acc[ai][bj][m][0], o1 = x1 + gv[bj][1] * acc[ai][bj][m][1];
;                     if (outf) { *(PG8_GAS f32x4*)(out + off + bj * HALF) = o0; *(PG8_GAS f32x4*)(out + off + bj * HALF + 4) = o1; }
;                     else { u32x4 w; w.x = cvt_pk_bf16(o0[0], o0[1]); w.y = cvt_pk_bf16(o0[2], o0[3]); w.z = cvt_pk_bf16(o1[0], o1[1]); w.w = cvt_pk_bf16(o1[2], o1[3]); *(PG8_GAS u32x4*)(outb + off + bj * HALF) = w; }
.LBB0_314:
	v_readlane_b32 s10, v251, 33
	v_lshl_or_b32 v200, s41, 8, v231
	v_ashrrev_i32_e32 v201, 31, v200
	v_mov_b32_e32 v76, s10
	v_readlane_b32 s10, v251, 34
	v_lshl_add_u32 v196, s40, 8, v183
	v_ashrrev_i32_e32 v197, 31, v196
	v_mov_b32_e32 v72, s10
	ds_read_b128 v[72:75], v72
	ds_read_b128 v[76:79], v76
	s_ashr_i32 s10, s40, 5
	s_mul_hi_i32 s25, s10, 0x9000
	s_mul_i32 s24, s10, 0x9000
	s_waitcnt lgkmcnt(0)
	v_lshl_add_u64 v[74:75], v[74:75], 0, s[24:25]
	v_lshl_add_u64 v[74:75], v[200:201], 2, v[74:75]
	global_load_dwordx4 v[202:205], v[74:75], off offset:16
	global_load_dwordx4 v[206:209], v[74:75], off
	global_load_dwordx4 v[156:159], v[74:75], off offset:528
	global_load_dwordx4 v[164:167], v[74:75], off offset:512
	v_lshl_add_u64 v[210:211], v[200:201], 1, v[76:77]
	v_lshlrev_b64 v[74:75], 11, v[196:197]
	v_or_b32_e32 v216, 16, v196
	v_lshl_add_u64 v[74:75], v[210:211], 0, v[74:75]
	v_ashrrev_i32_e32 v217, 31, v216
	global_load_dwordx4 v[234:237], v[74:75], off
	global_load_dwordx4 v[160:163], v[74:75], off offset:256
	v_lshlrev_b64 v[74:75], 11, v[216:217]
	v_or_b32_e32 v214, 32, v196
	v_lshl_add_u64 v[74:75], v[210:211], 0, v[74:75]
	v_ashrrev_i32_e32 v215, 31, v214
	global_load_dwordx4 v[152:155], v[74:75], off
	global_load_dwordx4 v[148:151], v[74:75], off offset:256
	v_lshlrev_b64 v[74:75], 11, v[214:215]
	v_or_b32_e32 v212, 48, v196
	v_lshl_add_u64 v[74:75], v[210:211], 0, v[74:75]
	v_ashrrev_i32_e32 v213, 31, v212
	global_load_dwordx4 v[144:147], v[74:75], off
	global_load_dwordx4 v[140:143], v[74:75], off offset:256
	v_lshlrev_b64 v[74:75], 11, v[212:213]
	v_lshl_add_u64 v[74:75], v[210:211], 0, v[74:75]
	global_load_dwordx4 v[136:139], v[74:75], off
	s_nop 0
	global_load_dwordx4 v[74:77], v[74:75], off offset:256
	v_readlane_b32 s10, v251, 36
	v_lshlrev_b64 v[220:221], 10, v[196:197]
	v_lshl_add_u64 v[220:221], v[220:221], 0, v[200:201]
	v_mov_b32_e32 v198, s10
	ds_read_b64 v[218:219], v198
	v_readlane_b32 s10, v251, 35
	s_mov_b64 s[38:39], -1
	v_readlane_b32 s14, v251, 49
	v_mov_b32_e32 v198, s10
	ds_read_b64 v[198:199], v198
	s_waitcnt lgkmcnt(0)
	v_readfirstlane_b32 s25, v219
	v_readfirstlane_b32 s24, v218
	s_and_b32 s10, s25, 4
	s_bitcmp1_b32 s25, 2
	v_lshl_add_u64 v[218:219], v[220:221], 2, v[78:79]
	s_cselect_b64 s[26:27], -1, 0
	s_cmp_eq_u32 s10, 0
	s_waitcnt vmcnt(0)
	v_pk_mul_f32 v[204:205], s[24:25], v[204:205] op_sel_hi:[0,1]
	v_pk_mul_f32 v[208:209], s[24:25], v[208:209] op_sel_hi:[0,1]
	v_pk_mul_f32 v[206:207], s[24:25], v[206:207] op_sel_hi:[0,1]
	v_pk_mul_f32 v[202:203], s[24:25], v[202:203] op_sel_hi:[0,1]
	v_lshlrev_b32_e32 v238, 16, v234
	v_and_b32_e32 v239, 0xffff0000, v234
	v_lshlrev_b32_e32 v234, 16, v235
	v_and_b32_e32 v235, 0xffff0000, v235
	v_lshlrev_b32_e32 v240, 16, v236
	v_and_b32_e32 v241, 0xffff0000, v236
	v_lshlrev_b32_e32 v236, 16, v237
	v_and_b32_e32 v237, 0xffff0000, v237
	v_pk_fma_f32 v[134:135], v[134:135], v[208:209], v[234:235]
	v_pk_fma_f32 v[132:133], v[132:133], v[206:207], v[238:239]
	v_pk_fma_f32 v[130:131], v[130:131], v[204:205], v[236:237]
	v_pk_fma_f32 v[128:129], v[128:129], v[202:203], v[240:241]
	s_cbranch_scc1 .LBB0_316
	s_mov_b64 s[38:39], 0
	global_store_dwordx4 v[218:219], v[132:135], off nt
	global_store_dwordx4 v[218:219], v[128:131], off offset:16 nt
.LBB0_316:
	s_andn2_b64 vcc, exec, s[38:39]
	v_lshl_add_u64 v[220:221], v[220:221], 1, v[72:73]
	s_cbranch_vccnz .LBB0_318
	v_cvt_pk_bf16_f32 v234, v132, v133
	v_cvt_pk_bf16_f32 v235, v134, v135
	v_cvt_pk_bf16_f32 v236, v128, v129
	v_cvt_pk_bf16_f32 v237, v130, v131
	global_store_dwordx4 v[220:221], v[234:237], off nt
.LBB0_318:
	s_mov_b32 s40, s24
	s_mov_b32 s41, s24
	s_mov_b32 s38, s24
	s_mov_b32 s39, s24
	v_pk_mul_f32 v[166:167], s[40:41], v[166:167]
	v_lshlrev_b32_e32 v234, 16, v160
	v_and_b32_e32 v235, 0xffff0000, v160
	v_lshlrev_b32_e32 v160, 16, v161
	v_and_b32_e32 v161, 0xffff0000, v161
	v_pk_mul_f32 v[164:165], s[38:39], v[164:165]
	v_pk_mul_f32 v[158:159], s[40:41], v[158:159]
	v_pk_mul_f32 v[156:157], s[38:39], v[156:157]
	v_lshlrev_b32_e32 v236, 16, v162
	v_and_b32_e32 v237, 0xffff0000, v162
	v_lshlrev_b32_e32 v162, 16, v163
	v_and_b32_e32 v163, 0xffff0000, v163
	v_pk_fma_f32 v[126:127], v[126:127], v[166:167], v[160:161]
	v_cndmask_b32_e64 v160, 0, 1, s[26:27]
	v_pk_fma_f32 v[124:125], v[124:125], v[164:165], v[234:235]
	v_pk_fma_f32 v[122:123], v[122:123], v[158:159], v[162:163]
	v_pk_fma_f32 v[120:121], v[120:121], v[156:157], v[236:237]
	v_cmp_ne_u32_e64 s[38:39], 1, v160
	s_andn2_b64 vcc, exec, s[26:27]
	s_mov_b64 s[26:27], -1
	s_cbranch_vccnz .LBB0_320
	s_mov_b64 s[26:27], 0
	global_store_dwordx4 v[218:219], v[124:127], off offset:512 nt
	global_store_dwordx4 v[218:219], v[120:123], off offset:528 nt
.LBB0_320:
	s_andn2_b64 vcc, exec, s[26:27]
	s_cbranch_vccnz .LBB0_322
	v_cvt_pk_bf16_f32 v160, v124, v125
	v_cvt_pk_bf16_f32 v161, v126, v127
	v_cvt_pk_bf16_f32 v162, v120, v121
	v_cvt_pk_bf16_f32 v163, v122, v123
	global_store_dwordx4 v[220:221], v[160:163], off offset:256 nt

; #define PG8_GAS __attribute__((address_space(1)))
;     __device__ __forceinline__ void operator()(const f32x4 (&acc)[2][2][4][2], const Unit& u, int wr, int wc, int fr, int fq) const {
;     ...
;             for (int m = 0; m < 4; ++m) { const int row = row0 + ai * HALF + m * 16; const size_t off = (size_t)row * 1024 + col0; float ss = 0.f;
; #pragma unroll
;                 for (int bj = 0; bj < 2; ++bj) {
;                     const u32x4 t = xa[ai][m][bj];
;                     const f32x4 x0 = (f32x4){__uint_as_float(t.x << 16), __uint_as_float(t.x & 0xffff0000u), __uint_as_float(t.y << 16), __uint_as_float(t.y & 0xffff0000u)};
;                     const f32x4 x1 = (f32x4){__uint_as_float(t.z << 16), __uint_as_float(t.z & 0xffff0000u), __uint_as_float(t.w << 16), __uint_as_float(t.w & 0xffff0000u)};
;                     const f32x4 o0 = x0 + gv[bj][0] * acc[ai][bj][m][0], o1 = x1 + gv[bj][1] * acc[ai][bj][m][1];
;                     if (outf) { *(PG8_GAS f32x4*)(out + off + bj * HALF) = o0; *(PG8_GAS f32x4*)(out + off + bj * HALF + 4) = o1; }
;                     else { u32x4 w; w.x = cvt_pk_bf16(o0[0], o0[1]); w.y = cvt_pk_bf16(o0[2], o0[3]); w.z = cvt_pk_bf16(o1[0], o1[1]); w.w = cvt_pk_bf16(o1[2], o1[3]); *(PG8_GAS u32x4*)(outb + off + bj * HALF) = w; }
.LBB0_326:
	s_waitcnt lgkmcnt(0)
	v_lshlrev_b64 v[120:121], 10, v[216:217]
	v_lshl_add_u64 v[122:123], v[120:121], 0, v[200:201]
	v_lshlrev_b32_e32 v124, 16, v152
	v_and_b32_e32 v125, 0xffff0000, v152
	v_lshlrev_b32_e32 v126, 16, v153
	v_and_b32_e32 v127, 0xffff0000, v153
	v_lshlrev_b32_e32 v128, 16, v154
	v_and_b32_e32 v129, 0xffff0000, v154
	v_lshlrev_b32_e32 v130, 16, v155
	v_and_b32_e32 v131, 0xffff0000, v155
	v_lshl_add_u64 v[120:121], v[122:123], 2, v[78:79]
	v_pk_fma_f32 v[118:119], v[118:119], v[208:209], v[126:127]
	v_pk_fma_f32 v[116:117], v[116:117], v[206:207], v[124:125]
	v_pk_fma_f32 v[114:115], v[114:115], v[204:205], v[130:131]
	v_pk_fma_f32 v[112:113], v[112:113], v[202:203], v[128:129]
	s_and_b64 vcc, exec, s[38:39]
	s_mov_b64 s[26:27], -1
	s_cbranch_vccnz .LBB0_328
	s_mov_b64 s[26:27], 0
	global_store_dwordx4 v[120:121], v[116:119], off nt
	global_store_dwordx4 v[120:121], v[112:115], off offset:16 nt
.LBB0_328:
	s_andn2_b64 vcc, exec, s[26:27]
	v_lshl_add_u64 v[122:123], v[122:123], 1, v[72:73]
	s_cbranch_vccnz .LBB0_330
	v_cvt_pk_bf16_f32 v124, v116, v117
	v_cvt_pk_bf16_f32 v125, v118, v119
	v_cvt_pk_bf16_f32 v126, v112, v113
	v_cvt_pk_bf16_f32 v127, v114, v115
	global_store_dwordx4 v[122:123], v[124:127], off nt

; #define PG8_GAS __attribute__((address_space(1)))
;     __device__ __forceinline__ void operator()(const f32x4 (&acc)[2][2][4][2], const Unit& u, int wr, int wc, int fr, int fq) const {
;     ...
;             for (int m = 0; m < 4; ++m) { const int row = row0 + ai * HALF + m * 16; const size_t off = (size_t)row * 1024 + col0; float ss = 0.f;
; #pragma unroll
;                 for (int bj = 0; bj < 2; ++bj) {
;                     const u32x4 t = xa[ai][m][bj];
;                     const f32x4 x0 = (f32x4){__uint_as_float(t.x << 16), __uint_as_float(t.x & 0xffff0000u), __uint_as_float(t.y << 16), __uint_as_float(t.y & 0xffff0000u)};
;                     const f32x4 x1 = (f32x4){__uint_as_float(t.z << 16), __uint_as_float(t.z & 0xffff0000u), __uint_as_float(t.w << 16), __uint_as_float(t.w & 0xffff0000u)};
;                     const f32x4 o0 = x0 + gv[bj][0] * acc[ai][bj][m][0], o1 = x1 + gv[bj][1] * acc[ai][bj][m][1];
;                     if (outf) { *(PG8_GAS f32x4*)(out + off + bj * HALF) = o0; *(PG8_GAS f32x4*)(out + off + bj * HALF + 4) = o1; }
;                     else { u32x4 w; w.x = cvt_pk_bf16(o0[0], o0[1]); w.y = cvt_pk_bf16(o0[2], o0[3]); w.z = cvt_pk_bf16(o1[0], o1[1]); w.w = cvt_pk_bf16(o1[2], o1[3]); *(PG8_GAS u32x4*)(outb + off + bj * HALF) = w; }
.LBB0_333:
	global_store_dwordx4 v[120:121], v[108:111], off offset:512 nt
	global_store_dwordx4 v[120:121], v[104:107], off offset:528 nt
	s_cbranch_execnz .LBB0_332
.LBB0_334:
	v_cvt_pk_bf16_f32 v124, v108, v109
	v_cvt_pk_bf16_f32 v125, v110, v111
	v_cvt_pk_bf16_f32 v126, v104, v105
	v_cvt_pk_bf16_f32 v127, v106, v107
	global_store_dwordx4 v[122:123], v[124:127], off offset:256 nt
	v_cndmask_b32_e64 v120, 0, 1, s[24:25]
	v_cmp_ne_u32_e64 s[40:41], 1, v120
	s_andn2_b64 vcc, exec, s[24:25]
	s_cbranch_vccnz .LBB0_338

; #define PG8_GAS __attribute__((address_space(1)))
;     __device__ __forceinline__ void operator()(const f32x4 (&acc)[2][2][4][2], const Unit& u, int wr, int wc, int fr, int fq) const {
;     ...
;             for (int m = 0; m < 4; ++m) { const int row = row0 + ai * HALF + m * 16; const size_t off = (size_t)row * 1024 + col0; float ss = 0.f;
; #pragma unroll
;                 for (int bj = 0; bj < 2; ++bj) {
;                     const u32x4 t = xa[ai][m][bj];
;                     const f32x4 x0 = (f32x4){__uint_as_float(t.x << 16), __uint_as_float(t.x & 0xffff0000u), __uint_as_float(t.y << 16), __uint_as_float(t.y & 0xffff0000u)};
;                     const f32x4 x1 = (f32x4){__uint_as_float(t.z << 16), __uint_as_float(t.z & 0xffff0000u), __uint_as_float(t.w << 16), __uint_as_float(t.w & 0xffff0000u)};
;                     const f32x4 o0 = x0 + gv[bj][0] * acc[ai][bj][m][0], o1 = x1 + gv[bj][1] * acc[ai][bj][m][1];
;                     if (outf) { *(PG8_GAS f32x4*)(out + off + bj * HALF) = o0; *(PG8_GAS f32x4*)(out + off + bj * HALF + 4) = o1; }
;                     else { u32x4 w; w.x = cvt_pk_bf16(o0[0], o0[1]); w.y = cvt_pk_bf16(o0[2], o0[3]); w.z = cvt_pk_bf16(o1[0], o1[1]); w.w = cvt_pk_bf16(o1[2], o1[3]); *(PG8_GAS u32x4*)(outb + off + bj * HALF) = w; }
.LBB0_338:
	s_waitcnt lgkmcnt(0)
	v_lshlrev_b64 v[104:105], 10, v[214:215]
	v_lshl_add_u64 v[106:107], v[104:105], 0, v[200:201]
	v_lshlrev_b32_e32 v108, 16, v144
	v_and_b32_e32 v109, 0xffff0000, v144
	v_lshlrev_b32_e32 v110, 16, v145
	v_and_b32_e32 v111, 0xffff0000, v145
	v_lshlrev_b32_e32 v112, 16, v146
	v_and_b32_e32 v113, 0xffff0000, v146
	v_lshlrev_b32_e32 v114, 16, v147
	v_and_b32_e32 v115, 0xffff0000, v147
	v_lshl_add_u64 v[104:105], v[106:107], 2, v[78:79]
	v_pk_fma_f32 v[102:103], v[102:103], v[208:209], v[110:111]
	v_pk_fma_f32 v[100:101], v[100:101], v[206:207], v[108:109]
	v_pk_fma_f32 v[98:99], v[98:99], v[204:205], v[114:115]
	v_pk_fma_f32 v[96:97], v[96:97], v[202:203], v[112:113]
	s_and_b64 vcc, exec, s[38:39]
	s_mov_b64 s[24:25], -1
	s_cbranch_vccnz .LBB0_340
	s_mov_b64 s[24:25], 0
	global_store_dwordx4 v[104:105], v[100:103], off nt
	global_store_dwordx4 v[104:105], v[96:99], off offset:16 nt
.LBB0_340:
	s_andn2_b64 vcc, exec, s[24:25]
	v_lshl_add_u64 v[106:107], v[106:107], 1, v[72:73]
	s_cbranch_vccnz .LBB0_342
	v_cvt_pk_bf16_f32 v108, v100, v101
	v_cvt_pk_bf16_f32 v109, v102, v103
	v_cvt_pk_bf16_f32 v110, v96, v97
	v_cvt_pk_bf16_f32 v111, v98, v99
	global_store_dwordx4 v[106:107], v[108:111], off nt

; #define PG8_GAS __attribute__((address_space(1)))
;     __device__ __forceinline__ void operator()(const f32x4 (&acc)[2][2][4][2], const Unit& u, int wr, int wc, int fr, int fq) const {
;     ...
;             for (int m = 0; m < 4; ++m) { const int row = row0 + ai * HALF + m * 16; const size_t off = (size_t)row * 1024 + col0; float ss = 0.f;
; #pragma unroll
;                 for (int bj = 0; bj < 2; ++bj) {
;                     const u32x4 t = xa[ai][m][bj];
;                     const f32x4 x0 = (f32x4){__uint_as_float(t.x << 16), __uint_as_float(t.x & 0xffff0000u), __uint_as_float(t.y << 16), __uint_as_float(t.y & 0xffff0000u)};
;                     const f32x4 x1 = (f32x4){__uint_as_float(t.z << 16), __uint_as_float(t.z & 0xffff0000u), __uint_as_float(t.w << 16), __uint_as_float(t.w & 0xffff0000u)};
;                     const f32x4 o0 = x0 + gv[bj][0] * acc[ai][bj][m][0], o1 = x1 + gv[bj][1] * acc[ai][bj][m][1];
;                     if (outf) { *(PG8_GAS f32x4*)(out + off + bj * HALF) = o0; *(PG8_GAS f32x4*)(out + off + bj * HALF + 4) = o1; }
;                     else { u32x4 w; w.x = cvt_pk_bf16(o0[0], o0[1]); w.y = cvt_pk_bf16(o0[2], o0[3]); w.z = cvt_pk_bf16(o1[0], o1[1]); w.w = cvt_pk_bf16(o1[2], o1[3]); *(PG8_GAS u32x4*)(outb + off + bj * HALF) = w; }
.LBB0_345:
	global_store_dwordx4 v[104:105], v[92:95], off offset:512 nt
	global_store_dwordx4 v[104:105], v[88:91], off offset:528 nt
	s_cbranch_execnz .LBB0_344
.LBB0_346:
	v_cvt_pk_bf16_f32 v108, v92, v93
	v_cvt_pk_bf16_f32 v109, v94, v95
	v_cvt_pk_bf16_f32 v110, v88, v89
	v_cvt_pk_bf16_f32 v111, v90, v91
	global_store_dwordx4 v[106:107], v[108:111], off offset:256 nt
	s_and_b64 vcc, exec, s[40:41]
	s_cbranch_vccnz .LBB0_350

; #define PG8_GAS __attribute__((address_space(1)))
;     __device__ __forceinline__ void operator()(const f32x4 (&acc)[2][2][4][2], const Unit& u, int wr, int wc, int fr, int fq) const {
;     ...
;             for (int m = 0; m < 4; ++m) { const int row = row0 + ai * HALF + m * 16; const size_t off = (size_t)row * 1024 + col0; float ss = 0.f;
; #pragma unroll
;                 for (int bj = 0; bj < 2; ++bj) {
;                     const u32x4 t = xa[ai][m][bj];
;                     const f32x4 x0 = (f32x4){__uint_as_float(t.x << 16), __uint_as_float(t.x & 0xffff0000u), __uint_as_float(t.y << 16), __uint_as_float(t.y & 0xffff0000u)};
;                     const f32x4 x1 = (f32x4){__uint_as_float(t.z << 16), __uint_as_float(t.z & 0xffff0000u), __uint_as_float(t.w << 16), __uint_as_float(t.w & 0xffff0000u)};
;                     const f32x4 o0 = x0 + gv[bj][0] * acc[ai][bj][m][0], o1 = x1 + gv[bj][1] * acc[ai][bj][m][1];
;                     if (outf) { *(PG8_GAS f32x4*)(out + off + bj * HALF) = o0; *(PG8_GAS f32x4*)(out + off + bj * HALF + 4) = o1; }
;                     else { u32x4 w; w.x = cvt_pk_bf16(o0[0], o0[1]); w.y = cvt_pk_bf16(o0[2], o0[3]); w.z = cvt_pk_bf16(o1[0], o1[1]); w.w = cvt_pk_bf16(o1[2], o1[3]); *(PG8_GAS u32x4*)(outb + off + bj * HALF) = w; }
.LBB0_350:
	s_waitcnt lgkmcnt(0)
	v_lshlrev_b64 v[88:89], 10, v[212:213]
	v_lshl_add_u64 v[90:91], v[88:89], 0, v[200:201]
	v_lshlrev_b32_e32 v92, 16, v136
	v_and_b32_e32 v93, 0xffff0000, v136
	v_lshlrev_b32_e32 v94, 16, v137
	v_and_b32_e32 v95, 0xffff0000, v137
	v_lshlrev_b32_e32 v96, 16, v138
	v_and_b32_e32 v97, 0xffff0000, v138
	v_lshlrev_b32_e32 v98, 16, v139
	v_and_b32_e32 v99, 0xffff0000, v139
	v_lshl_add_u64 v[88:89], v[90:91], 2, v[78:79]
	v_pk_fma_f32 v[86:87], v[86:87], v[208:209], v[94:95]
	v_pk_fma_f32 v[84:85], v[84:85], v[206:207], v[92:93]
	v_pk_fma_f32 v[82:83], v[82:83], v[204:205], v[98:99]
	v_pk_fma_f32 v[80:81], v[80:81], v[202:203], v[96:97]
	s_and_b64 vcc, exec, s[38:39]
	s_mov_b64 s[24:25], -1
	s_cbranch_vccnz .LBB0_352
	s_mov_b64 s[24:25], 0
	global_store_dwordx4 v[88:89], v[84:87], off nt
	global_store_dwordx4 v[88:89], v[80:83], off offset:16 nt
.LBB0_352:
	s_andn2_b64 vcc, exec, s[24:25]
	v_lshl_add_u64 v[90:91], v[90:91], 1, v[72:73]
	s_cbranch_vccnz .LBB0_354
	v_cvt_pk_bf16_f32 v92, v84, v85
	v_cvt_pk_bf16_f32 v93, v86, v87
	v_cvt_pk_bf16_f32 v94, v80, v81
	v_cvt_pk_bf16_f32 v95, v82, v83
	global_store_dwordx4 v[90:91], v[92:95], off nt

; #define PG8_GAS __attribute__((address_space(1)))
;     __device__ __forceinline__ void operator()(const f32x4 (&acc)[2][2][4][2], const Unit& u, int wr, int wc, int fr, int fq) const {
;     ...
;             for (int m = 0; m < 4; ++m) { const int row = row0 + ai * HALF + m * 16; const size_t off = (size_t)row * 1024 + col0; float ss = 0.f;
; #pragma unroll
;                 for (int bj = 0; bj < 2; ++bj) {
;                     const u32x4 t = xa[ai][m][bj];
;                     const f32x4 x0 = (f32x4){__uint_as_float(t.x << 16), __uint_as_float(t.x & 0xffff0000u), __uint_as_float(t.y << 16), __uint_as_float(t.y & 0xffff0000u)};
;                     const f32x4 x1 = (f32x4){__uint_as_float(t.z << 16), __uint_as_float(t.z & 0xffff0000u), __uint_as_float(t.w << 16), __uint_as_float(t.w & 0xffff0000u)};
;                     const f32x4 o0 = x0 + gv[bj][0] * acc[ai][bj][m][0], o1 = x1 + gv[bj][1] * acc[ai][bj][m][1];
;                     if (outf) { *(PG8_GAS f32x4*)(out + off + bj * HALF) = o0; *(PG8_GAS f32x4*)(out + off + bj * HALF + 4) = o1; }
;                     else { u32x4 w; w.x = cvt_pk_bf16(o0[0], o0[1]); w.y = cvt_pk_bf16(o0[2], o0[3]); w.z = cvt_pk_bf16(o1[0], o1[1]); w.w = cvt_pk_bf16(o1[2], o1[3]); *(PG8_GAS u32x4*)(outb + off + bj * HALF) = w; }
.LBB0_357:
	global_store_dwordx4 v[88:89], v[68:71], off offset:512 nt
	global_store_dwordx4 v[88:89], v[64:67], off offset:528 nt
	s_cbranch_execnz .LBB0_356
.LBB0_358:
	v_cvt_pk_bf16_f32 v74, v68, v69
	v_cvt_pk_bf16_f32 v75, v70, v71
	v_cvt_pk_bf16_f32 v76, v64, v65
	v_cvt_pk_bf16_f32 v77, v66, v67
	global_store_dwordx4 v[90:91], v[74:77], off offset:256 nt
	s_and_b64 vcc, exec, s[40:41]
	s_cbranch_vccnz .LBB0_362

; #define PG8_GAS __attribute__((address_space(1)))
;     __device__ __forceinline__ void operator()(const f32x4 (&acc)[2][2][4][2], const Unit& u, int wr, int wc, int fr, int fq) const {
;     ...
;                 for (int bj = 0; bj < 2; ++bj) xa[ai][m][bj] = *(const PG8_GAS u32x4*)(xinb + (size_t)(row0 + ai * HALF + m * 16) * 1024 + col0 + bj * HALF);
; #pragma unroll
;             for (int m = 0; m < 4; ++m) { const int row = row0 + ai * HALF + m * 16; const size_t off = (size_t)row * 1024 + col0; float ss = 0.f;
; #pragma unroll
;                 for (int bj = 0; bj < 2; ++bj) {
;                     const u32x4 t = xa[ai][m][bj];
;                     const f32x4 x0 = (f32x4){__uint_as_float(t.x << 16), __uint_as_float(t.x & 0xffff0000u), __uint_as_float(t.y << 16), __uint_as_float(t.y & 0xffff0000u)};
;                     const f32x4 x1 = (f32x4){__uint_as_float(t.z << 16), __uint_as_float(t.z & 0xffff0000u), __uint_as_float(t.w << 16), __uint_as_float(t.w & 0xffff0000u)};
;                     const f32x4 o0 = x0 + gv[bj][0] * acc[ai][bj][m][0], o1 = x1 + gv[bj][1] * acc[ai][bj][m][1];
;                     if (outf) { *(PG8_GAS f32x4*)(out + off + bj * HALF) = o0; *(PG8_GAS f32x4*)(out + off + bj * HALF + 4) = o1; }
;                     else { u32x4 w; w.x = cvt_pk_bf16(o0[0], o0[1]); w.y = cvt_pk_bf16(o0[2], o0[3]); w.z = cvt_pk_bf16(o1[0], o1[1]); w.w = cvt_pk_bf16(o1[2], o1[3]); *(PG8_GAS u32x4*)(outb + off + bj * HALF) = w; }
.LBB0_362:
	v_add_u32_e32 v102, 0x80, v196
	v_ashrrev_i32_e32 v103, 31, v102
	s_waitcnt lgkmcnt(0)
	v_lshlrev_b64 v[64:65], 11, v[102:103]
	v_add_u32_e32 v100, 0x90, v196
	v_lshl_add_u64 v[64:65], v[210:211], 0, v[64:65]
	v_ashrrev_i32_e32 v101, 31, v100
	global_load_dwordx4 v[106:109], v[64:65], off
	global_load_dwordx4 v[92:95], v[64:65], off offset:256
	v_lshlrev_b64 v[64:65], 11, v[100:101]
	v_add_u32_e32 v98, 0xa0, v196
	v_lshl_add_u64 v[64:65], v[210:211], 0, v[64:65]
	v_ashrrev_i32_e32 v99, 31, v98
	global_load_dwordx4 v[88:91], v[64:65], off
	global_load_dwordx4 v[84:87], v[64:65], off offset:256
	v_lshlrev_b64 v[64:65], 11, v[98:99]
	v_add_u32_e32 v96, 0xb0, v196
	v_lshl_add_u64 v[64:65], v[210:211], 0, v[64:65]
	v_ashrrev_i32_e32 v97, 31, v96
	global_load_dwordx4 v[80:83], v[64:65], off
	global_load_dwordx4 v[74:77], v[64:65], off offset:256
	v_lshlrev_b64 v[64:65], 11, v[96:97]
	v_lshl_add_u64 v[64:65], v[210:211], 0, v[64:65]
	global_load_dwordx4 v[68:71], v[64:65], off
	s_nop 0
	global_load_dwordx4 v[64:67], v[64:65], off offset:256
	v_lshlrev_b64 v[102:103], 10, v[102:103]
	v_lshl_add_u64 v[104:105], v[102:103], 0, v[200:201]
	s_and_b64 vcc, exec, s[38:39]
	v_lshl_add_u64 v[102:103], v[104:105], 2, v[78:79]
	s_mov_b64 s[24:25], -1
	s_waitcnt vmcnt(7)
	v_lshlrev_b32_e32 v110, 16, v106
	v_and_b32_e32 v111, 0xffff0000, v106
	v_lshlrev_b32_e32 v106, 16, v107
	v_and_b32_e32 v107, 0xffff0000, v107
	v_lshlrev_b32_e32 v112, 16, v108
	v_and_b32_e32 v113, 0xffff0000, v108
	v_lshlrev_b32_e32 v108, 16, v109
	v_and_b32_e32 v109, 0xffff0000, v109
	v_pk_fma_f32 v[62:63], v[62:63], v[208:209], v[106:107]
	v_pk_fma_f32 v[60:61], v[60:61], v[206:207], v[110:111]
	v_pk_fma_f32 v[58:59], v[58:59], v[204:205], v[108:109]
	v_pk_fma_f32 v[56:57], v[56:57], v[202:203], v[112:113]
	s_cbranch_vccnz .LBB0_364
	s_mov_b64 s[24:25], 0
	global_store_dwordx4 v[102:103], v[60:63], off nt
	global_store_dwordx4 v[102:103], v[56:59], off offset:16 nt
.LBB0_364:
	s_andn2_b64 vcc, exec, s[24:25]
	v_lshl_add_u64 v[104:105], v[104:105], 1, v[72:73]
	s_cbranch_vccnz .LBB0_366
	v_cvt_pk_bf16_f32 v106, v60, v61
	v_cvt_pk_bf16_f32 v107, v62, v63
	v_cvt_pk_bf16_f32 v108, v56, v57
	v_cvt_pk_bf16_f32 v109, v58, v59
	global_store_dwordx4 v[104:105], v[106:109], off nt

; #define PG8_GAS __attribute__((address_space(1)))
;     __device__ __forceinline__ void operator()(const f32x4 (&acc)[2][2][4][2], const Unit& u, int wr, int wc, int fr, int fq) const {
;     ...
;             for (int m = 0; m < 4; ++m) { const int row = row0 + ai * HALF + m * 16; const size_t off = (size_t)row * 1024 + col0; float ss = 0.f;
; #pragma unroll
;                 for (int bj = 0; bj < 2; ++bj) {
;                     const u32x4 t = xa[ai][m][bj];
;                     const f32x4 x0 = (f32x4){__uint_as_float(t.x << 16), __uint_as_float(t.x & 0xffff0000u), __uint_as_float(t.y << 16), __uint_as_float(t.y & 0xffff0000u)};
;                     const f32x4 x1 = (f32x4){__uint_as_float(t.z << 16), __uint_as_float(t.z & 0xffff0000u), __uint_as_float(t.w << 16), __uint_as_float(t.w & 0xffff0000u)};
;                     const f32x4 o0 = x0 + gv[bj][0] * acc[ai][bj][m][0], o1 = x1 + gv[bj][1] * acc[ai][bj][m][1];
;                     if (outf) { *(PG8_GAS f32x4*)(out + off + bj * HALF) = o0; *(PG8_GAS f32x4*)(out + off + bj * HALF + 4) = o1; }
;                     else { u32x4 w; w.x = cvt_pk_bf16(o0[0], o0[1]); w.y = cvt_pk_bf16(o0[2], o0[3]); w.z = cvt_pk_bf16(o1[0], o1[1]); w.w = cvt_pk_bf16(o1[2], o1[3]); *(PG8_GAS u32x4*)(outb + off + bj * HALF) = w; }
.LBB0_369:
	global_store_dwordx4 v[102:103], v[52:55], off offset:512 nt
	global_store_dwordx4 v[102:103], v[48:51], off offset:528 nt
	s_cbranch_execnz .LBB0_368
.LBB0_370:
	v_cvt_pk_bf16_f32 v92, v52, v53
	v_cvt_pk_bf16_f32 v93, v54, v55
	v_cvt_pk_bf16_f32 v94, v48, v49
	v_cvt_pk_bf16_f32 v95, v50, v51
	global_store_dwordx4 v[104:105], v[92:95], off offset:256 nt
	s_and_b64 vcc, exec, s[40:41]
	s_cbranch_vccnz .LBB0_374

; #define PG8_GAS __attribute__((address_space(1)))
;     __device__ __forceinline__ void operator()(const f32x4 (&acc)[2][2][4][2], const Unit& u, int wr, int wc, int fr, int fq) const {
;     ...
;             for (int m = 0; m < 4; ++m) { const int row = row0 + ai * HALF + m * 16; const size_t off = (size_t)row * 1024 + col0; float ss = 0.f;
; #pragma unroll
;                 for (int bj = 0; bj < 2; ++bj) {
;                     const u32x4 t = xa[ai][m][bj];
;                     const f32x4 x0 = (f32x4){__uint_as_float(t.x << 16), __uint_as_float(t.x & 0xffff0000u), __uint_as_float(t.y << 16), __uint_as_float(t.y & 0xffff0000u)};
;                     const f32x4 x1 = (f32x4){__uint_as_float(t.z << 16), __uint_as_float(t.z & 0xffff0000u), __uint_as_float(t.w << 16), __uint_as_float(t.w & 0xffff0000u)};
;                     const f32x4 o0 = x0 + gv[bj][0] * acc[ai][bj][m][0], o1 = x1 + gv[bj][1] * acc[ai][bj][m][1];
;                     if (outf) { *(PG8_GAS f32x4*)(out + off + bj * HALF) = o0; *(PG8_GAS f32x4*)(out + off + bj * HALF + 4) = o1; }
;                     else { u32x4 w; w.x = cvt_pk_bf16(o0[0], o0[1]); w.y = cvt_pk_bf16(o0[2], o0[3]); w.z = cvt_pk_bf16(o1[0], o1[1]); w.w = cvt_pk_bf16(o1[2], o1[3]); *(PG8_GAS u32x4*)(outb + off + bj * HALF) = w; }
.LBB0_374:
	s_waitcnt lgkmcnt(0)
	v_lshlrev_b64 v[48:49], 10, v[100:101]
	v_lshl_add_u64 v[50:51], v[48:49], 0, v[200:201]
	s_waitcnt vmcnt(5)
	v_lshlrev_b32_e32 v52, 16, v88
	v_and_b32_e32 v53, 0xffff0000, v88
	v_lshlrev_b32_e32 v54, 16, v89
	v_and_b32_e32 v55, 0xffff0000, v89
	v_lshlrev_b32_e32 v56, 16, v90
	v_and_b32_e32 v57, 0xffff0000, v90
	v_lshlrev_b32_e32 v58, 16, v91
	v_and_b32_e32 v59, 0xffff0000, v91
	v_lshl_add_u64 v[48:49], v[50:51], 2, v[78:79]
	v_pk_fma_f32 v[46:47], v[46:47], v[208:209], v[54:55]
	v_pk_fma_f32 v[44:45], v[44:45], v[206:207], v[52:53]
	v_pk_fma_f32 v[42:43], v[42:43], v[204:205], v[58:59]
	v_pk_fma_f32 v[40:41], v[40:41], v[202:203], v[56:57]
	s_and_b64 vcc, exec, s[38:39]
	s_mov_b64 s[24:25], -1
	s_cbranch_vccnz .LBB0_376
	s_mov_b64 s[24:25], 0
	global_store_dwordx4 v[48:49], v[44:47], off nt
	global_store_dwordx4 v[48:49], v[40:43], off offset:16 nt
.LBB0_376:
	s_andn2_b64 vcc, exec, s[24:25]
	v_lshl_add_u64 v[50:51], v[50:51], 1, v[72:73]
	s_cbranch_vccnz .LBB0_378
	v_cvt_pk_bf16_f32 v52, v44, v45
	v_cvt_pk_bf16_f32 v53, v46, v47
	v_cvt_pk_bf16_f32 v54, v40, v41
	v_cvt_pk_bf16_f32 v55, v42, v43
	global_store_dwordx4 v[50:51], v[52:55], off nt

; #define PG8_GAS __attribute__((address_space(1)))
;     __device__ __forceinline__ void operator()(const f32x4 (&acc)[2][2][4][2], const Unit& u, int wr, int wc, int fr, int fq) const {
;     ...
;             for (int m = 0; m < 4; ++m) { const int row = row0 + ai * HALF + m * 16; const size_t off = (size_t)row * 1024 + col0; float ss = 0.f;
; #pragma unroll
;                 for (int bj = 0; bj < 2; ++bj) {
;                     const u32x4 t = xa[ai][m][bj];
;                     const f32x4 x0 = (f32x4){__uint_as_float(t.x << 16), __uint_as_float(t.x & 0xffff0000u), __uint_as_float(t.y << 16), __uint_as_float(t.y & 0xffff0000u)};
;                     const f32x4 x1 = (f32x4){__uint_as_float(t.z << 16), __uint_as_float(t.z & 0xffff0000u), __uint_as_float(t.w << 16), __uint_as_float(t.w & 0xffff0000u)};
;                     const f32x4 o0 = x0 + gv[bj][0] * acc[ai][bj][m][0], o1 = x1 + gv[bj][1] * acc[ai][bj][m][1];
;                     if (outf) { *(PG8_GAS f32x4*)(out + off + bj * HALF) = o0; *(PG8_GAS f32x4*)(out + off + bj * HALF + 4) = o1; }
;                     else { u32x4 w; w.x = cvt_pk_bf16(o0[0], o0[1]); w.y = cvt_pk_bf16(o0[2], o0[3]); w.z = cvt_pk_bf16(o1[0], o1[1]); w.w = cvt_pk_bf16(o1[2], o1[3]); *(PG8_GAS u32x4*)(outb + off + bj * HALF) = w; }
.LBB0_381:
	global_store_dwordx4 v[48:49], v[36:39], off offset:512 nt
	global_store_dwordx4 v[48:49], v[32:35], off offset:528 nt
	s_cbranch_execnz .LBB0_380
.LBB0_382:
	v_cvt_pk_bf16_f32 v52, v36, v37
	v_cvt_pk_bf16_f32 v53, v38, v39
	v_cvt_pk_bf16_f32 v54, v32, v33
	v_cvt_pk_bf16_f32 v55, v34, v35
	global_store_dwordx4 v[50:51], v[52:55], off offset:256 nt
	s_and_b64 vcc, exec, s[40:41]
	s_cbranch_vccnz .LBB0_386

; #define PG8_GAS __attribute__((address_space(1)))
;     __device__ __forceinline__ void operator()(const f32x4 (&acc)[2][2][4][2], const Unit& u, int wr, int wc, int fr, int fq) const {
;     ...
;             for (int m = 0; m < 4; ++m) { const int row = row0 + ai * HALF + m * 16; const size_t off = (size_t)row * 1024 + col0; float ss = 0.f;
; #pragma unroll
;                 for (int bj = 0; bj < 2; ++bj) {
;                     const u32x4 t = xa[ai][m][bj];
;                     const f32x4 x0 = (f32x4){__uint_as_float(t.x << 16), __uint_as_float(t.x & 0xffff0000u), __uint_as_float(t.y << 16), __uint_as_float(t.y & 0xffff0000u)};
;                     const f32x4 x1 = (f32x4){__uint_as_float(t.z << 16), __uint_as_float(t.z & 0xffff0000u), __uint_as_float(t.w << 16), __uint_as_float(t.w & 0xffff0000u)};
;                     const f32x4 o0 = x0 + gv[bj][0] * acc[ai][bj][m][0], o1 = x1 + gv[bj][1] * acc[ai][bj][m][1];
;                     if (outf) { *(PG8_GAS f32x4*)(out + off + bj * HALF) = o0; *(PG8_GAS f32x4*)(out + off + bj * HALF + 4) = o1; }
;                     else { u32x4 w; w.x = cvt_pk_bf16(o0[0], o0[1]); w.y = cvt_pk_bf16(o0[2], o0[3]); w.z = cvt_pk_bf16(o1[0], o1[1]); w.w = cvt_pk_bf16(o1[2], o1[3]); *(PG8_GAS u32x4*)(outb + off + bj * HALF) = w; }
.LBB0_386:
	s_waitcnt lgkmcnt(0)
	v_lshlrev_b64 v[32:33], 10, v[98:99]
	v_lshl_add_u64 v[34:35], v[32:33], 0, v[200:201]
	s_waitcnt vmcnt(3)
	v_lshlrev_b32_e32 v36, 16, v80
	v_and_b32_e32 v37, 0xffff0000, v80
	v_lshlrev_b32_e32 v38, 16, v81
	v_and_b32_e32 v39, 0xffff0000, v81
	v_lshlrev_b32_e32 v40, 16, v82
	v_and_b32_e32 v41, 0xffff0000, v82
	v_lshlrev_b32_e32 v42, 16, v83
	v_and_b32_e32 v43, 0xffff0000, v83
	v_lshl_add_u64 v[32:33], v[34:35], 2, v[78:79]
	v_pk_fma_f32 v[30:31], v[30:31], v[208:209], v[38:39]
	v_pk_fma_f32 v[28:29], v[28:29], v[206:207], v[36:37]
	v_pk_fma_f32 v[26:27], v[26:27], v[204:205], v[42:43]
	v_pk_fma_f32 v[24:25], v[24:25], v[202:203], v[40:41]
	s_and_b64 vcc, exec, s[38:39]
	s_mov_b64 s[24:25], -1
	s_cbranch_vccnz .LBB0_388
	s_mov_b64 s[24:25], 0
	global_store_dwordx4 v[32:33], v[28:31], off nt
	global_store_dwordx4 v[32:33], v[24:27], off offset:16 nt
.LBB0_388:
	s_andn2_b64 vcc, exec, s[24:25]
	v_lshl_add_u64 v[34:35], v[34:35], 1, v[72:73]
	s_cbranch_vccnz .LBB0_390
	v_cvt_pk_bf16_f32 v36, v28, v29
	v_cvt_pk_bf16_f32 v37, v30, v31
	v_cvt_pk_bf16_f32 v38, v24, v25
	v_cvt_pk_bf16_f32 v39, v26, v27
	global_store_dwordx4 v[34:35], v[36:39], off nt

; #define PG8_GAS __attribute__((address_space(1)))
;     __device__ __forceinline__ void operator()(const f32x4 (&acc)[2][2][4][2], const Unit& u, int wr, int wc, int fr, int fq) const {
;     ...
;             for (int m = 0; m < 4; ++m) { const int row = row0 + ai * HALF + m * 16; const size_t off = (size_t)row * 1024 + col0; float ss = 0.f;
; #pragma unroll
;                 for (int bj = 0; bj < 2; ++bj) {
;                     const u32x4 t = xa[ai][m][bj];
;                     const f32x4 x0 = (f32x4){__uint_as_float(t.x << 16), __uint_as_float(t.x & 0xffff0000u), __uint_as_float(t.y << 16), __uint_as_float(t.y & 0xffff0000u)};
;                     const f32x4 x1 = (f32x4){__uint_as_float(t.z << 16), __uint_as_float(t.z & 0xffff0000u), __uint_as_float(t.w << 16), __uint_as_float(t.w & 0xffff0000u)};
;                     const f32x4 o0 = x0 + gv[bj][0] * acc[ai][bj][m][0], o1 = x1 + gv[bj][1] * acc[ai][bj][m][1];
;                     if (outf) { *(PG8_GAS f32x4*)(out + off + bj * HALF) = o0; *(PG8_GAS f32x4*)(out + off + bj * HALF + 4) = o1; }
;                     else { u32x4 w; w.x = cvt_pk_bf16(o0[0], o0[1]); w.y = cvt_pk_bf16(o0[2], o0[3]); w.z = cvt_pk_bf16(o1[0], o1[1]); w.w = cvt_pk_bf16(o1[2], o1[3]); *(PG8_GAS u32x4*)(outb + off + bj * HALF) = w; }
.LBB0_393:
	global_store_dwordx4 v[32:33], v[20:23], off offset:512 nt
	global_store_dwordx4 v[32:33], v[16:19], off offset:528 nt
	s_cbranch_execnz .LBB0_392
.LBB0_394:
	v_cvt_pk_bf16_f32 v36, v20, v21
	v_cvt_pk_bf16_f32 v37, v22, v23
	v_cvt_pk_bf16_f32 v38, v16, v17
	v_cvt_pk_bf16_f32 v39, v18, v19
	global_store_dwordx4 v[34:35], v[36:39], off offset:256 nt
	s_and_b64 vcc, exec, s[40:41]
	s_cbranch_vccnz .LBB0_398

; #define PG8_GAS __attribute__((address_space(1)))
;     __device__ __forceinline__ void operator()(const f32x4 (&acc)[2][2][4][2], const Unit& u, int wr, int wc, int fr, int fq) const {
;     ...
;             for (int m = 0; m < 4; ++m) { const int row = row0 + ai * HALF + m * 16; const size_t off = (size_t)row * 1024 + col0; float ss = 0.f;
; #pragma unroll
;                 for (int bj = 0; bj < 2; ++bj) {
;                     const u32x4 t = xa[ai][m][bj];
;                     const f32x4 x0 = (f32x4){__uint_as_float(t.x << 16), __uint_as_float(t.x & 0xffff0000u), __uint_as_float(t.y << 16), __uint_as_float(t.y & 0xffff0000u)};
;                     const f32x4 x1 = (f32x4){__uint_as_float(t.z << 16), __uint_as_float(t.z & 0xffff0000u), __uint_as_float(t.w << 16), __uint_as_float(t.w & 0xffff0000u)};
;                     const f32x4 o0 = x0 + gv[bj][0] * acc[ai][bj][m][0], o1 = x1 + gv[bj][1] * acc[ai][bj][m][1];
;                     if (outf) { *(PG8_GAS f32x4*)(out + off + bj * HALF) = o0; *(PG8_GAS f32x4*)(out + off + bj * HALF + 4) = o1; }
;                     else { u32x4 w; w.x = cvt_pk_bf16(o0[0], o0[1]); w.y = cvt_pk_bf16(o0[2], o0[3]); w.z = cvt_pk_bf16(o1[0], o1[1]); w.w = cvt_pk_bf16(o1[2], o1[3]); *(PG8_GAS u32x4*)(outb + off + bj * HALF) = w; }
.LBB0_398:
	s_waitcnt lgkmcnt(0)
	v_lshlrev_b64 v[16:17], 10, v[96:97]
	v_lshl_add_u64 v[18:19], v[16:17], 0, v[200:201]
	s_waitcnt vmcnt(1)
	v_lshlrev_b32_e32 v20, 16, v68
	v_and_b32_e32 v21, 0xffff0000, v68
	v_lshlrev_b32_e32 v22, 16, v69
	v_and_b32_e32 v23, 0xffff0000, v69
	v_lshlrev_b32_e32 v24, 16, v70
	v_and_b32_e32 v25, 0xffff0000, v70
	v_lshlrev_b32_e32 v26, 16, v71
	v_and_b32_e32 v27, 0xffff0000, v71
	v_lshl_add_u64 v[16:17], v[18:19], 2, v[78:79]
	v_pk_fma_f32 v[14:15], v[14:15], v[208:209], v[22:23]
	v_pk_fma_f32 v[12:13], v[12:13], v[206:207], v[20:21]
	v_pk_fma_f32 v[10:11], v[10:11], v[204:205], v[26:27]
	v_pk_fma_f32 v[8:9], v[8:9], v[202:203], v[24:25]
	s_and_b64 vcc, exec, s[38:39]
	s_mov_b64 s[24:25], -1
	s_cbranch_vccnz .LBB0_400
	s_mov_b64 s[24:25], 0
	global_store_dwordx4 v[16:17], v[12:15], off nt
	global_store_dwordx4 v[16:17], v[8:11], off offset:16 nt
.LBB0_400:
	s_andn2_b64 vcc, exec, s[24:25]
	v_lshl_add_u64 v[18:19], v[18:19], 1, v[72:73]
	s_cbranch_vccnz .LBB0_402
	v_cvt_pk_bf16_f32 v20, v12, v13
	v_cvt_pk_bf16_f32 v21, v14, v15
	v_cvt_pk_bf16_f32 v22, v8, v9
	v_cvt_pk_bf16_f32 v23, v10, v11
	global_store_dwordx4 v[18:19], v[20:23], off nt

; #define PG8_GAS __attribute__((address_space(1)))
;     __device__ __forceinline__ void operator()(const f32x4 (&acc)[2][2][4][2], const Unit& u, int wr, int wc, int fr, int fq) const {
;     ...
;             for (int m = 0; m < 4; ++m) { const int row = row0 + ai * HALF + m * 16; const size_t off = (size_t)row * 1024 + col0; float ss = 0.f;
; #pragma unroll
;                 for (int bj = 0; bj < 2; ++bj) {
;                     const u32x4 t = xa[ai][m][bj];
;                     const f32x4 x0 = (f32x4){__uint_as_float(t.x << 16), __uint_as_float(t.x & 0xffff0000u), __uint_as_float(t.y << 16), __uint_as_float(t.y & 0xffff0000u)};
;                     const f32x4 x1 = (f32x4){__uint_as_float(t.z << 16), __uint_as_float(t.z & 0xffff0000u), __uint_as_float(t.w << 16), __uint_as_float(t.w & 0xffff0000u)};
;                     const f32x4 o0 = x0 + gv[bj][0] * acc[ai][bj][m][0], o1 = x1 + gv[bj][1] * acc[ai][bj][m][1];
;                     if (outf) { *(PG8_GAS f32x4*)(out + off + bj * HALF) = o0; *(PG8_GAS f32x4*)(out + off + bj * HALF + 4) = o1; }
;                     else { u32x4 w; w.x = cvt_pk_bf16(o0[0], o0[1]); w.y = cvt_pk_bf16(o0[2], o0[3]); w.z = cvt_pk_bf16(o1[0], o1[1]); w.w = cvt_pk_bf16(o1[2], o1[3]); *(PG8_GAS u32x4*)(outb + off + bj * HALF) = w; }
.LBB0_405:
	global_store_dwordx4 v[16:17], v[4:7], off offset:512 nt
	global_store_dwordx4 v[16:17], v[0:3], off offset:528 nt
	s_cbranch_execnz .LBB0_404
.LBB0_406:
	v_cvt_pk_bf16_f32 v20, v4, v5
	v_cvt_pk_bf16_f32 v21, v6, v7
	v_cvt_pk_bf16_f32 v22, v0, v1
	v_cvt_pk_bf16_f32 v23, v2, v3
	global_store_dwordx4 v[18:19], v[20:23], off offset:256 nt
	s_and_b64 vcc, exec, s[40:41]
	s_cbranch_vccnz .LBB0_410
